# LRU: gate-tile LDS reads before the aggregate barrier, restage barrier dropped (2 barriers per chunk instead of 3)
# baseline (speedup 1.0000x reference)
.LBB0_432:
	s_or_b64 exec, exec, s[40:41]
	v_cndmask_b32_e64 v73, v74, 1.0, s[14:15]
	v_cndmask_b32_e64 v71, v71, 0, s[14:15]
	s_waitcnt lgkmcnt(4)
	v_fmac_f32_e32 v40, v71, v34
	v_mul_f32_e32 v34, v73, v34
	v_cndmask_b32_e64 v34, v73, v34, s[18:19]
	v_cndmask_b32_e64 v40, v71, v40, s[18:19]
	s_waitcnt lgkmcnt(2)
	v_fmac_f32_e32 v35, v40, v72
	v_mul_f32_e32 v71, v34, v72
	v_cndmask_b32_e64 v34, v34, v71, s[20:21]
	v_cndmask_b32_e64 v35, v40, v35, s[20:21]
	v_mul_f32_e32 v40, v39, v34
	v_fmac_f32_e32 v33, v39, v35
	v_mul_f32_e32 v39, v32, v34
	v_fmac_f32_e32 v29, v32, v35
	v_mul_f32_e32 v32, v31, v34
	v_fmac_f32_e32 v30, v31, v35
	v_mul_f32_e32 v31, v69, v34
	v_fmac_f32_e32 v28, v69, v35
	v_cndmask_b32_e64 v34, v70, 1.0, s[14:15]
	v_cndmask_b32_e64 v35, v63, 0, s[14:15]
	v_fmac_f32_e32 v61, v35, v42
	v_mul_f32_e32 v42, v34, v42
	v_cndmask_b32_e64 v34, v34, v42, s[18:19]
	v_cndmask_b32_e64 v35, v35, v61, s[18:19]
	v_fmac_f32_e32 v43, v35, v68
	v_mul_f32_e32 v42, v34, v68
	v_cndmask_b32_e64 v34, v34, v42, s[20:21]
	v_cndmask_b32_e64 v35, v35, v43, s[20:21]
	v_mul_f32_e32 v63, v55, v34
	v_fmac_f32_e32 v41, v55, v35
	v_mul_f32_e32 v61, v56, v34
	v_fmac_f32_e32 v37, v56, v35
	v_mul_f32_e32 v56, v65, v34
	v_fmac_f32_e32 v38, v65, v35
	v_mul_f32_e32 v55, v67, v34
	v_fmac_f32_e32 v36, v67, v35
	v_cndmask_b32_e64 v34, v66, 1.0, s[14:15]
	v_cndmask_b32_e64 v35, v220, 0, s[14:15]
	v_fmac_f32_e32 v219, v35, v50
	v_mul_f32_e32 v42, v34, v50
	v_cndmask_b32_e64 v34, v34, v42, s[18:19]
	v_cndmask_b32_e64 v35, v35, v219, s[18:19]
	v_fmac_f32_e32 v51, v35, v64
	v_mul_f32_e32 v42, v34, v64
	v_cndmask_b32_e64 v34, v34, v42, s[20:21]
	v_cndmask_b32_e64 v35, v35, v51, s[20:21]
	v_mul_f32_e32 v66, v216, v34
	v_fmac_f32_e32 v49, v216, v35
	v_mul_f32_e32 v65, v48, v34
	v_fmac_f32_e32 v45, v48, v35
	v_mul_f32_e32 v64, v217, v34
	v_fmac_f32_e32 v46, v217, v35
	v_mul_f32_e32 v48, v218, v34
	v_fmac_f32_e32 v44, v218, v35
	v_cndmask_b32_e64 v34, v62, 1.0, s[14:15]
	v_cndmask_b32_e64 v35, v215, 0, s[14:15]
	v_fmac_f32_e32 v214, v35, v58
	v_mul_f32_e32 v42, v34, v58
	v_cndmask_b32_e64 v34, v34, v42, s[18:19]
	v_cndmask_b32_e64 v35, v35, v214, s[18:19]
	v_fmac_f32_e32 v59, v35, v60
	v_mul_f32_e32 v42, v34, v60
	v_cndmask_b32_e64 v34, v34, v42, s[20:21]
	v_cndmask_b32_e64 v35, v35, v59, s[20:21]
	v_mul_f32_e32 v60, v76, v34
	v_fmac_f32_e32 v57, v76, v35
	v_mul_f32_e32 v62, v99, v34
	v_mul_f32_e32 v67, v212, v34
	v_mul_f32_e32 v76, v213, v34
	v_add_u32_e32 v34, v151, v47
	ds_read_u16 v221, v187
	ds_read_u16 v222, v187 offset:144
	ds_read_u16 v190, v187 offset:32
	ds_read_u16 v216, v187 offset:64
	ds_read_u16 v217, v187 offset:176
	ds_read_u16 v218, v187 offset:208
	ds_read_u16 v219, v187 offset:240
	ds_read_u16 v220, v187 offset:96
	ds_read_u16 v230, v187 offset:288
	ds_read_u16 v69, v187 offset:432
	ds_read_u16 v224, v187 offset:320
	ds_read_u16 v225, v187 offset:464
	ds_read_u16 v226, v187 offset:352
	ds_read_u16 v227, v187 offset:496
	ds_read_u16 v228, v187 offset:528
	ds_read_u16 v229, v187 offset:384
	s_waitcnt lgkmcnt(0)
	s_barrier
	ds_read_b64 v[50:51], v34
	v_fmac_f32_e32 v53, v99, v35
	v_fmac_f32_e32 v54, v212, v35
	v_fmac_f32_e32 v52, v213, v35
	v_add_u32_e32 v34, v152, v47
	v_add_u32_e32 v35, v153, v47
	v_add_u32_e32 v42, v154, v47
	ds_read_b64 v[58:59], v34
	ds_read_b64 v[34:35], v35
	ds_read_b64 v[42:43], v42
	v_cndmask_b32_e64 v68, 0, v104, s[22:23]
	s_waitcnt lgkmcnt(3)
	v_fmac_f32_e32 v51, v104, v50
	v_cndmask_b32_e64 v50, v68, v51, s[24:25]
	s_waitcnt lgkmcnt(2)
	v_fmac_f32_e32 v59, v51, v58
	s_waitcnt lgkmcnt(0)
	v_lshlrev_b32_e32 v221, 16, v221
	v_mul_f32_e32 v51, 0xbfb8aa3b, v221
	s_waitcnt lgkmcnt(6)
	v_lshlrev_b32_e32 v222, 16, v222
	v_exp_f32_e32 v51, v51
	v_mul_f32_e32 v58, 0xbfb8aa3b, v222
	v_exp_f32_e32 v68, v58
	v_add_u32_e32 v70, v160, v47
	v_add_f32_e32 v51, 1.0, v51
	v_rcp_f32_e32 v223, v51
	v_add_f32_e32 v51, 1.0, v68
	s_waitcnt lgkmcnt(7)
	v_lshlrev_b32_e32 v230, 16, v230
	v_mul_f32_e32 v68, 0xbfb8aa3b, v230
	s_waitcnt lgkmcnt(6)
	v_lshlrev_b32_e32 v231, 16, v69
	v_exp_f32_e32 v68, v68
	v_mul_f32_e32 v69, 0xbfb8aa3b, v231
	v_exp_f32_e32 v69, v69
	v_rcp_f32_e32 v232, v51
	v_add_f32_e32 v51, 1.0, v68
	v_rcp_f32_e32 v233, v51
	v_add_f32_e32 v51, 1.0, v69
	v_rcp_f32_e32 v234, v51
	v_add_u32_e32 v51, v159, v47
	ds_read_b64 v[68:69], v51
	v_add_u32_e32 v72, v161, v47
	v_add_u32_e32 v74, v162, v47
	ds_read_b64 v[70:71], v70
	ds_read_b64 v[72:73], v72
	ds_read_b64 v[74:75], v74
	v_cndmask_b32_e64 v51, 0, v105, s[22:23]
	s_waitcnt lgkmcnt(3)
	v_fmac_f32_e32 v69, v105, v68
	v_cndmask_b32_e64 v51, v51, v69, s[24:25]
	s_waitcnt lgkmcnt(2)
	v_fmac_f32_e32 v71, v69, v70
	v_cndmask_b32_e64 v99, v50, v59, s[26:27]
	v_mul_f32_e32 v50, v59, v34
	v_add_u32_e32 v34, v155, v47
	v_cndmask_b32_e64 v235, v51, v71, s[26:27]
	s_waitcnt lgkmcnt(1)
	v_mul_f32_e32 v51, v71, v72
	v_mov_b32_e32 v72, v35
	v_pk_add_f32 v[68:69], v[50:51], v[72:73]
	ds_read_b64 v[50:51], v34
	v_mov_b32_e32 v34, v42
	s_waitcnt lgkmcnt(1)
	v_mov_b32_e32 v35, v74
	v_mov_b32_e32 v74, v43
	v_add_u32_e32 v104, v156, v47
	v_add_u32_e32 v105, v163, v47
	v_add_u32_e32 v212, v164, v47
	v_add_u32_e32 v214, v165, v47
	v_cndmask_b32_e64 v72, v99, v68, s[28:29]
	v_pk_fma_f32 v[70:71], v[68:69], v[34:35], v[74:75]
	v_add_u32_e32 v112, v157, v47
	v_add_u32_e32 v113, v158, v47
	v_add_u32_e32 v236, v166, v47
	v_cndmask_b32_e64 v68, v72, v70, s[30:31]
	ds_read_b64 v[72:73], v105
	ds_read_b64 v[74:75], v104
	ds_read_b64 v[104:105], v112
	ds_read_b64 v[34:35], v113
	ds_read_b64 v[212:213], v212
	ds_read_b64 v[214:215], v214
	ds_read_b64 v[42:43], v236
	s_waitcnt lgkmcnt(7)
	v_mov_b32_e32 v112, v50
	s_waitcnt lgkmcnt(6)
	v_mov_b32_e32 v113, v72
	v_mov_b32_e32 v72, v51
	v_pk_fma_f32 v[72:73], v[70:71], v[112:113], v[72:73]
	s_waitcnt lgkmcnt(5)
	v_mov_b32_e32 v50, v74
	s_waitcnt lgkmcnt(2)
	v_mov_b32_e32 v51, v212
	v_mov_b32_e32 v212, v75
	v_cndmask_b32_e64 v68, v68, v72, s[34:35]
	v_pk_fma_f32 v[74:75], v[72:73], v[50:51], v[212:213]
	v_mov_b32_e32 v50, v104
	s_waitcnt lgkmcnt(1)
	v_mov_b32_e32 v51, v214
	v_mov_b32_e32 v214, v105
	v_cndmask_b32_e64 v68, v68, v74, s[36:37]
	v_pk_fma_f32 v[50:51], v[74:75], v[50:51], v[214:215]
	v_lshl_add_u64 v[58:59], v[108:109], 0, s[62:63]
	v_cndmask_b32_e64 v68, v68, v50, s[38:39]
	v_fmac_f32_e32 v57, v60, v68
	v_mul_f32_e32 v57, v57, v221
	v_mul_f32_e32 v57, v57, v223
	v_fmac_f32_e32 v53, v62, v68
	v_bfe_u32 v60, v57, 16, 1
	v_mul_f32_e32 v53, v53, v222
	v_add3_u32 v57, v57, v60, s73
	v_mul_f32_e32 v53, v53, v232
	global_store_short_d16_hi v[58:59], v57, off
	v_bfe_u32 v57, v53, 16, 1
	v_add3_u32 v53, v53, v57, s73
	v_fmac_f32_e32 v54, v67, v68
	global_store_short_d16_hi v[58:59], v53, off offset:2048
	v_mul_f32_e32 v53, v54, v230
	v_mul_f32_e32 v53, v53, v233
	s_movk_i32 s40, 0x1000
	v_fmac_f32_e32 v52, v76, v68
	v_bfe_u32 v54, v53, 16, 1
	v_add_co_u32_e32 v104, vcc, s40, v58
	v_mul_f32_e32 v52, v52, v231
	v_add3_u32 v53, v53, v54, s73
	v_addc_co_u32_e32 v105, vcc, 0, v59, vcc
	v_mul_f32_e32 v52, v52, v234
	global_store_short_d16_hi v[104:105], v53, off
	v_bfe_u32 v53, v52, 16, 1
	v_add3_u32 v52, v52, v53, s73
	global_store_short_d16_hi v[104:105], v52, off offset:2048
	v_cndmask_b32_e64 v52, v235, v69, s[28:29]
	v_lshlrev_b32_e32 v53, 16, v190
	v_cndmask_b32_e64 v52, v52, v71, s[30:31]
	v_mul_f32_e32 v54, 0xbfb8aa3b, v53
	v_cndmask_b32_e64 v52, v52, v73, s[34:35]
	v_exp_f32_e32 v54, v54
	v_cndmask_b32_e64 v52, v52, v75, s[36:37]
	v_cndmask_b32_e64 v52, v52, v51, s[38:39]
	v_fmac_f32_e32 v49, v66, v52
	v_mul_f32_e32 v49, v49, v53
	v_add_f32_e32 v53, 1.0, v54
	v_rcp_f32_e32 v53, v53
	v_lshlrev_b32_e32 v54, 16, v217
	v_mul_f32_e32 v57, 0xbfb8aa3b, v54
	v_exp_f32_e32 v57, v57
	v_mul_f32_e32 v49, v49, v53
	v_bfe_u32 v53, v49, 16, 1
	v_add3_u32 v49, v49, v53, s73
	v_add_f32_e32 v53, 1.0, v57
	v_rcp_f32_e32 v53, v53
	v_fmac_f32_e32 v45, v65, v52
	v_mul_f32_e32 v45, v45, v54
	global_store_short_d16_hi v[58:59], v49, off offset:32
	v_mul_f32_e32 v45, v45, v53
	v_bfe_u32 v49, v45, 16, 1
	v_add3_u32 v45, v45, v49, s73
	v_lshlrev_b32_e32 v49, 16, v224
	v_mul_f32_e32 v53, 0xbfb8aa3b, v49
	v_exp_f32_e32 v53, v53
	v_fmac_f32_e32 v46, v64, v52
	global_store_short_d16_hi v[58:59], v45, off offset:2080
	v_mul_f32_e32 v45, v46, v49
	v_add_f32_e32 v46, 1.0, v53
	v_rcp_f32_e32 v46, v46
	v_lshlrev_b32_e32 v49, 16, v225
	v_mul_f32_e32 v53, 0xbfb8aa3b, v49
	v_exp_f32_e32 v53, v53
	v_mul_f32_e32 v45, v45, v46
	v_bfe_u32 v46, v45, 16, 1
	v_add3_u32 v45, v45, v46, s73
	v_add_f32_e32 v46, 1.0, v53
	v_rcp_f32_e32 v46, v46
	v_fmac_f32_e32 v44, v48, v52
	v_mul_f32_e32 v44, v44, v49
	global_store_short_d16_hi v[104:105], v45, off offset:32
	v_mul_f32_e32 v44, v44, v46
	v_bfe_u32 v45, v44, 16, 1
	v_add3_u32 v44, v44, v45, s73
	global_store_short_d16_hi v[104:105], v44, off offset:2080
	v_add_u32_e32 v44, v167, v47
	ds_read_b64 v[44:45], v44
	v_add_u32_e32 v48, v168, v47
	v_add_u32_e32 v52, v169, v47
	v_add_u32_e32 v54, v170, v47
	ds_read_b64 v[48:49], v48
	ds_read_b64 v[52:53], v52
	ds_read_b64 v[64:65], v54
	v_cndmask_b32_e64 v46, 0, v110, s[22:23]
	s_waitcnt lgkmcnt(3)
	v_fmac_f32_e32 v45, v110, v44
	v_lshlrev_b32_e32 v62, 16, v216
	v_cndmask_b32_e64 v44, v46, v45, s[24:25]
	s_waitcnt lgkmcnt(2)
	v_fmac_f32_e32 v49, v45, v48
	v_mul_f32_e32 v45, 0xbfb8aa3b, v62
	v_lshlrev_b32_e32 v76, 16, v218
	v_exp_f32_e32 v45, v45
	v_mul_f32_e32 v48, 0xbfb8aa3b, v76
	v_exp_f32_e32 v48, v48
	v_lshlrev_b32_e32 v112, 16, v226
	v_add_f32_e32 v45, 1.0, v45
	v_rcp_f32_e32 v99, v45
	v_add_f32_e32 v45, 1.0, v48
	v_mul_f32_e32 v48, 0xbfb8aa3b, v112
	v_lshlrev_b32_e32 v113, 16, v227
	v_cndmask_b32_e64 v46, v44, v49, s[26:27]
	s_waitcnt lgkmcnt(1)
	v_mul_f32_e32 v44, v49, v52
	v_exp_f32_e32 v48, v48
	v_mul_f32_e32 v49, 0xbfb8aa3b, v113
	v_exp_f32_e32 v49, v49
	v_rcp_f32_e32 v190, v45
	v_add_f32_e32 v45, 1.0, v48
	v_rcp_f32_e32 v212, v45
	v_add_f32_e32 v45, 1.0, v49
	v_rcp_f32_e32 v213, v45
	v_add_u32_e32 v45, v176, v47
	ds_read_b64 v[48:49], v45
	v_add_u32_e32 v52, v177, v47
	v_add_u32_e32 v68, v178, v47
	v_add_u32_e32 v70, v179, v47
	ds_read_b64 v[66:67], v52
	ds_read_b64 v[68:69], v68
	ds_read_b64 v[70:71], v70
	v_cndmask_b32_e64 v45, 0, v111, s[22:23]
	s_waitcnt lgkmcnt(3)
	v_fmac_f32_e32 v49, v111, v48
	v_add_u32_e32 v54, v171, v47
	v_cndmask_b32_e64 v45, v45, v49, s[24:25]
	s_waitcnt lgkmcnt(2)
	v_fmac_f32_e32 v67, v49, v66
	v_cndmask_b32_e64 v214, v45, v67, s[26:27]
	s_waitcnt lgkmcnt(1)
	v_mul_f32_e32 v45, v67, v68
	v_mov_b32_e32 v68, v53
	ds_read_b64 v[48:49], v54
	v_pk_add_f32 v[52:53], v[44:45], v[68:69]
	v_mov_b32_e32 v44, v64
	s_waitcnt lgkmcnt(1)
	v_mov_b32_e32 v45, v70
	v_mov_b32_e32 v70, v65
	v_add_u32_e32 v57, v172, v47
	v_add_u32_e32 v60, v173, v47
	v_add_u32_e32 v72, v175, v47
	v_add_u32_e32 v66, v180, v47
	v_add_u32_e32 v73, v181, v47
	v_add_u32_e32 v110, v182, v47
	v_add_u32_e32 v47, v183, v47
	v_cndmask_b32_e64 v46, v46, v52, s[28:29]
	v_pk_fma_f32 v[64:65], v[52:53], v[44:45], v[70:71]
	ds_read_b64 v[66:67], v66
	ds_read_b64 v[68:69], v57
	ds_read_b64 v[70:71], v60
	ds_read_b64 v[44:45], v72
	v_cndmask_b32_e64 v52, v46, v64, s[30:31]
	ds_read_b64 v[74:75], v73
	ds_read_b64 v[110:111], v110
	ds_read_b64 v[46:47], v47
	s_waitcnt lgkmcnt(7)
	v_mov_b32_e32 v72, v48
	s_waitcnt lgkmcnt(6)
	v_mov_b32_e32 v73, v66
	v_mov_b32_e32 v66, v49
	v_pk_fma_f32 v[66:67], v[64:65], v[72:73], v[66:67]
	s_waitcnt lgkmcnt(5)
	v_mov_b32_e32 v48, v68
	s_waitcnt lgkmcnt(2)
	v_mov_b32_e32 v49, v74
	v_mov_b32_e32 v74, v69
	v_cndmask_b32_e64 v52, v52, v66, s[34:35]
	v_pk_fma_f32 v[68:69], v[66:67], v[48:49], v[74:75]
	v_mov_b32_e32 v48, v70
	s_waitcnt lgkmcnt(1)
	v_mov_b32_e32 v49, v110
	v_mov_b32_e32 v110, v71
	v_cndmask_b32_e64 v52, v52, v68, s[36:37]
	v_pk_fma_f32 v[48:49], v[68:69], v[48:49], v[110:111]
	s_nop 0
	v_cndmask_b32_e64 v52, v52, v48, s[38:39]
	v_fmac_f32_e32 v41, v63, v52
	v_mul_f32_e32 v41, v41, v62
	v_mul_f32_e32 v41, v41, v99
	v_fmac_f32_e32 v37, v61, v52
	v_bfe_u32 v54, v41, 16, 1
	v_mul_f32_e32 v37, v37, v76
	v_add3_u32 v41, v41, v54, s73
	v_mul_f32_e32 v37, v37, v190
	global_store_short_d16_hi v[58:59], v41, off offset:64
	v_bfe_u32 v41, v37, 16, 1
	v_add3_u32 v37, v37, v41, s73
	v_fmac_f32_e32 v38, v56, v52
	global_store_short_d16_hi v[58:59], v37, off offset:2112
	v_mul_f32_e32 v37, v38, v112
	v_mul_f32_e32 v37, v37, v212
	v_fmac_f32_e32 v36, v55, v52
	v_bfe_u32 v38, v37, 16, 1
	v_mul_f32_e32 v36, v36, v113
	v_add3_u32 v37, v37, v38, s73
	v_mul_f32_e32 v36, v36, v213
	global_store_short_d16_hi v[104:105], v37, off offset:64
	v_bfe_u32 v37, v36, 16, 1
	v_add3_u32 v36, v36, v37, s73
	global_store_short_d16_hi v[104:105], v36, off offset:2112
	v_cndmask_b32_e64 v36, v214, v53, s[28:29]
	v_lshlrev_b32_e32 v37, 16, v220
	v_cndmask_b32_e64 v36, v36, v65, s[30:31]
	v_mul_f32_e32 v38, 0xbfb8aa3b, v37
	v_cndmask_b32_e64 v36, v36, v67, s[34:35]
	v_exp_f32_e32 v38, v38
	v_cndmask_b32_e64 v36, v36, v69, s[36:37]
	v_cndmask_b32_e64 v36, v36, v49, s[38:39]
	v_fmac_f32_e32 v33, v40, v36
	v_mul_f32_e32 v33, v33, v37
	v_add_f32_e32 v37, 1.0, v38
	v_rcp_f32_e32 v37, v37
	v_lshlrev_b32_e32 v38, 16, v219
	v_mul_f32_e32 v40, 0xbfb8aa3b, v38
	v_exp_f32_e32 v40, v40
	v_mul_f32_e32 v33, v33, v37
	v_bfe_u32 v37, v33, 16, 1
	v_add3_u32 v33, v33, v37, s73
	v_add_f32_e32 v37, 1.0, v40
	v_rcp_f32_e32 v37, v37
	v_fmac_f32_e32 v29, v39, v36
	v_mul_f32_e32 v29, v29, v38
	global_store_short_d16_hi v[58:59], v33, off offset:96
	v_mul_f32_e32 v29, v29, v37
	v_bfe_u32 v33, v29, 16, 1
	v_add3_u32 v29, v29, v33, s73
	v_lshlrev_b32_e32 v33, 16, v229
	v_mul_f32_e32 v37, 0xbfb8aa3b, v33
	v_exp_f32_e32 v37, v37
	v_fmac_f32_e32 v30, v32, v36
	global_store_short_d16_hi v[58:59], v29, off offset:2144
	v_mul_f32_e32 v29, v30, v33
	v_add_f32_e32 v30, 1.0, v37
	v_rcp_f32_e32 v30, v30
	v_lshlrev_b32_e32 v32, 16, v228
	v_mul_f32_e32 v33, 0xbfb8aa3b, v32
	v_exp_f32_e32 v33, v33
	v_mul_f32_e32 v29, v29, v30
	v_bfe_u32 v30, v29, 16, 1
	v_add3_u32 v29, v29, v30, s73
	v_add_f32_e32 v30, 1.0, v33
	v_rcp_f32_e32 v30, v30
	v_fmac_f32_e32 v28, v31, v36
	v_mul_f32_e32 v28, v28, v32
	global_store_short_d16_hi v[104:105], v29, off offset:96
	v_mul_f32_e32 v28, v28, v30
	v_bfe_u32 v29, v28, 16, 1
	v_add3_u32 v28, v28, v29, s73
	global_store_short_d16_hi v[104:105], v28, off offset:2144
	s_waitcnt lgkmcnt(0)
	s_waitcnt vmcnt(18)
	ds_write_b128 v95, v[0:3]
	ds_write_b128 v195, v[8:11]
	ds_write_b128 v196, v[4:7]
	s_and_saveexec_b64 s[40:41], s[8:9]
	ds_write_b128 v197, v[16:19]
	s_or_b64 exec, exec, s[40:41]
	s_and_saveexec_b64 s[40:41], s[12:13]
	s_cbranch_execz .LBB0_403
	ds_write_b128 v198, v[12:15]
	s_branch .LBB0_403
